# DA tile loop software-pipelined fast path (QK of subtile B overlapped with PV of A, LDS reads hoisted) + NSA top-k bit search without redundant ballot re-masking
# speedup vs baseline: 1.0344x; 1.0344x over previous
; __device__ __forceinline__ unsigned pk2(float lo, float hi) { const f32x2_t v = {lo, hi}; const bf16v2_t b = __builtin_convertvector(v, bf16v2_t); return __builtin_bit_cast(unsigned, b); }
; __device__ __forceinline__ void phase_da(const Params& p, int layer, LAS unsigned char* lds, const bf16_t* Z, bf16_t* Mixed, int tid, int wid, int lane) {
;     ...
;             l1 = L1[0]; l2 = L2[0];
;             const float i1 = 1.f / l1, i2 = lam / l2;
;             float ss = 0.f;
; #pragma unroll
;             for (int i = 0; i < 16; ++i) { oa0[i] = oa0[i] * i1 - ob0[i] * i2; oa1[i] = oa1[i] * i1 - ob1[i] * i2; ss += oa0[i] * oa0[i] + oa1[i] * oa1[i]; }
;             ss += __shfl_xor(ss, 32);
;             const float rn = rsqrtf(ss * (1.f / 64.f) + EPSN) * (1.f - lam_init);
;             bf16_t* orow = Mixed + row * DM + 256 + hd * 64;
; #pragma unroll
;             for (int g4 = 0; g4 < 4; ++g4) {
;                 const int dv = 8 * g4 + 4 * h; const f32x4 ga = *(const f32x4*)(gain + hd * 64 + dv), gb = *(const f32x4*)(gain + hd * 64 + 32 + dv);
;                 u32x2 wa, wb;
;                 wa.x = pk2(oa0[4 * g4 + 0] * rn * ga.x, oa0[4 * g4 + 1] * rn * ga.y); wa.y = pk2(oa0[4 * g4 + 2] * rn * ga.z, oa0[4 * g4 + 3] * rn * ga.w);
;                 wb.x = pk2(oa1[4 * g4 + 0] * rn * gb.x, oa1[4 * g4 + 1] * rn * gb.y); wb.y = pk2(oa1[4 * g4 + 2] * rn * gb.z, oa1[4 * g4 + 3] * rn * gb.w);
;                 *(u32x2*)(orow + dv) = wa; *(u32x2*)(orow + 32 + dv) = wb;
.LBB0_233:
	v_lshlrev_b32_e32 v140, 4, v187
	v_add_u32_e32 v141, 0x19000, v140
	v_add_u32_e32 v140, 0x9000, v140
	ds_read_b128 v[190:193], v140
	ds_read_b128 v[194:197], v140 offset:8192
	ds_read_b128 v[198:201], v140 offset:16384
	ds_read_b128 v[202:205], v140 offset:24576
	ds_read_b128 v[206:209], v140 offset:32768
	ds_read_b128 v[210:213], v140 offset:40960
	ds_read_b128 v[214:217], v140 offset:49152
	ds_read_b128 v[218:221], v140 offset:57344
	ds_read_b128 v[222:225], v141
	ds_read_b128 v[226:229], v141 offset:8192
	ds_read_b128 v[242:245], v141 offset:16384
	ds_read_b128 v[172:175], v141 offset:24576
	ds_read_b64 v[238:239], v141 offset:32768
	s_nop 3
	v_div_scale_f32 v98, s[6:7], v2, v2, 1.0
	v_rcp_f32_e32 v99, v98
	s_waitcnt lgkmcnt(0)
	s_barrier
	v_fma_f32 v100, -v98, v99, 1.0
	v_fmac_f32_e32 v99, v100, v99
	v_div_scale_f32 v100, vcc, 1.0, v2, 1.0
	v_mul_f32_e32 v101, v100, v99
	v_fma_f32 v102, -v98, v101, v100
	v_fmac_f32_e32 v101, v102, v99
	v_fma_f32 v98, -v98, v101, v100
	v_div_scale_f32 v100, s[6:7], v18, v18, v247
	v_rcp_f32_e32 v103, v100
	v_div_fmas_f32 v98, v98, v99, v101
	v_div_fixup_f32 v102, v98, v2, 1.0
	s_mov_b64 s[6:7], 0x10000200
	v_fma_f32 v98, -v100, v103, 1.0
	v_fmac_f32_e32 v103, v98, v103
	v_div_scale_f32 v98, vcc, v247, v18, v247
	v_mul_f32_e32 v99, v98, v103
	v_fma_f32 v101, -v100, v99, v98
	v_fmac_f32_e32 v99, v101, v103
	v_fma_f32 v98, -v100, v99, v98
	v_div_fmas_f32 v98, v98, v103, v99
	v_div_fixup_f32 v104, v98, v18, v247
	v_pk_mul_f32 v[94:95], v[94:95], v[104:105] op_sel_hi:[1,0]
	global_load_dwordx4 v[98:101], v[216:217], off
	v_pk_fma_f32 v[46:47], v[102:103], v[46:47], v[94:95] op_sel_hi:[0,1,1] neg_lo:[0,0,1] neg_hi:[0,0,1]
	v_pk_mul_f32 v[94:95], v[96:97], v[104:105] op_sel_hi:[1,0]
	v_pk_mul_f32 v[52:53], v[52:53], v[104:105] op_sel_hi:[1,0]
	v_pk_fma_f32 v[48:49], v[102:103], v[48:49], v[94:95] op_sel_hi:[0,1,1] neg_lo:[0,0,1] neg_hi:[0,0,1]
	global_load_dwordx4 v[94:97], v[216:217], off offset:128
	v_pk_fma_f32 v[52:53], v[102:103], v[68:69], v[52:53] op_sel_hi:[0,1,1] neg_lo:[0,0,1] neg_hi:[0,0,1]
	v_pk_mul_f32 v[50:51], v[50:51], v[104:105] op_sel_hi:[1,0]
	v_pk_mul_f32 v[68:69], v[82:83], v[104:105] op_sel_hi:[1,0]
	v_pk_fma_f32 v[50:51], v[102:103], v[66:67], v[50:51] op_sel_hi:[0,1,1] neg_lo:[0,0,1] neg_hi:[0,0,1]
	v_pk_mul_f32 v[66:67], v[84:85], v[104:105] op_sel_hi:[1,0]
	v_pk_fma_f32 v[34:35], v[102:103], v[34:35], v[68:69] op_sel_hi:[0,1,1] neg_lo:[0,0,1] neg_hi:[0,0,1]
	v_pk_fma_f32 v[36:37], v[102:103], v[36:37], v[66:67] op_sel_hi:[0,1,1] neg_lo:[0,0,1] neg_hi:[0,0,1]
	v_pk_mul_f32 v[68:69], v[34:35], v[34:35]
	v_pk_mul_f32 v[56:57], v[56:57], v[104:105] op_sel_hi:[1,0]
	v_pk_mul_f32 v[66:67], v[36:37], v[36:37]
	v_pk_fma_f32 v[68:69], v[50:51], v[50:51], v[68:69]
	v_pk_fma_f32 v[56:57], v[102:103], v[72:73], v[56:57] op_sel_hi:[0,1,1] neg_lo:[0,0,1] neg_hi:[0,0,1]
	v_pk_mul_f32 v[72:73], v[86:87], v[104:105] op_sel_hi:[1,0]
	v_pk_fma_f32 v[66:67], v[52:53], v[52:53], v[66:67]
	v_pk_mul_f32 v[54:55], v[54:55], v[104:105] op_sel_hi:[1,0]
	v_pk_fma_f32 v[72:73], v[102:103], v[38:39], v[72:73] op_sel_hi:[0,1,1] neg_lo:[0,0,1] neg_hi:[0,0,1]
	v_add_f32_e32 v68, v68, v69
	v_pk_fma_f32 v[54:55], v[102:103], v[70:71], v[54:55] op_sel_hi:[0,1,1] neg_lo:[0,0,1] neg_hi:[0,0,1]
	v_pk_mul_f32 v[70:71], v[88:89], v[104:105] op_sel_hi:[1,0]
	v_pk_mul_f32 v[38:39], v[72:73], v[72:73]
	v_add_f32_e32 v66, v66, v68
	v_pk_fma_f32 v[70:71], v[102:103], v[40:41], v[70:71] op_sel_hi:[0,1,1] neg_lo:[0,0,1] neg_hi:[0,0,1]
	v_pk_fma_f32 v[38:39], v[54:55], v[54:55], v[38:39]
	v_pk_mul_f32 v[60:61], v[60:61], v[104:105] op_sel_hi:[1,0]
	v_add_f32_e32 v66, v67, v66
	v_pk_mul_f32 v[40:41], v[70:71], v[70:71]
	v_pk_fma_f32 v[60:61], v[102:103], v[76:77], v[60:61] op_sel_hi:[0,1,1] neg_lo:[0,0,1] neg_hi:[0,0,1]
	v_pk_mul_f32 v[76:77], v[90:91], v[104:105] op_sel_hi:[1,0]
	v_add_f32_e32 v38, v38, v66
	v_pk_fma_f32 v[40:41], v[56:57], v[56:57], v[40:41]
	v_pk_mul_f32 v[58:59], v[58:59], v[104:105] op_sel_hi:[1,0]
	v_pk_fma_f32 v[42:43], v[102:103], v[42:43], v[76:77] op_sel_hi:[0,1,1] neg_lo:[0,0,1] neg_hi:[0,0,1]
	v_add_f32_e32 v38, v39, v38
	v_pk_fma_f32 v[58:59], v[102:103], v[74:75], v[58:59] op_sel_hi:[0,1,1] neg_lo:[0,0,1] neg_hi:[0,0,1]
	v_pk_mul_f32 v[74:75], v[92:93], v[104:105] op_sel_hi:[1,0]
	v_pk_mul_f32 v[76:77], v[42:43], v[42:43]
	v_add_f32_e32 v38, v40, v38
	v_pk_fma_f32 v[44:45], v[102:103], v[44:45], v[74:75] op_sel_hi:[0,1,1] neg_lo:[0,0,1] neg_hi:[0,0,1]
	v_pk_fma_f32 v[76:77], v[58:59], v[58:59], v[76:77]
	v_add_f32_e32 v38, v41, v38
	v_pk_mul_f32 v[74:75], v[44:45], v[44:45]
	v_add_f32_e32 v38, v76, v38
	v_pk_mul_f32 v[62:63], v[62:63], v[104:105] op_sel_hi:[1,0]
	v_pk_fma_f32 v[74:75], v[60:61], v[60:61], v[74:75]
	v_add_f32_e32 v38, v77, v38
	v_pk_fma_f32 v[62:63], v[102:103], v[78:79], v[62:63] op_sel_hi:[0,1,1] neg_lo:[0,0,1] neg_hi:[0,0,1]
	v_pk_mul_f32 v[78:79], v[46:47], v[46:47]
	v_add_f32_e32 v38, v74, v38
	v_pk_fma_f32 v[78:79], v[62:63], v[62:63], v[78:79]
	v_pk_mul_f32 v[64:65], v[64:65], v[104:105] op_sel_hi:[1,0]
	v_add_f32_e32 v38, v75, v38
	v_pk_fma_f32 v[64:65], v[102:103], v[80:81], v[64:65] op_sel_hi:[0,1,1] neg_lo:[0,0,1] neg_hi:[0,0,1]
	v_pk_mul_f32 v[80:81], v[48:49], v[48:49]
	v_add_f32_e32 v38, v78, v38
	v_pk_fma_f32 v[80:81], v[64:65], v[64:65], v[80:81]
	v_add_f32_e32 v38, v79, v38
	v_add_f32_e32 v38, v80, v38
	v_add_f32_e32 v40, v81, v38
	ds_bpermute_b32 v41, v239, v40
	v_lshlrev_b64 v[38:39], 11, v[228:229]
	v_lshl_add_u64 v[38:39], s[8:9], 0, v[38:39]
	v_lshl_add_u64 v[38:39], v[38:39], 0, s[26:27]
	v_lshl_add_u64 v[38:39], v[38:39], 0, v[0:1]
	s_waitcnt lgkmcnt(0)
; __device__ __forceinline__ unsigned pk2(float lo, float hi) { const f32x2_t v = {lo, hi}; const bf16v2_t b = __builtin_convertvector(v, bf16v2_t); return __builtin_bit_cast(unsigned, b); }
; __device__ __forceinline__ void phase_da(const Params& p, int layer, LAS unsigned char* lds, const bf16_t* Z, bf16_t* Mixed, int tid, int wid, int lane) {
;     ...
;             ss += __shfl_xor(ss, 32);
;             const float rn = rsqrtf(ss * (1.f / 64.f) + EPSN) * (1.f - lam_init);
;             bf16_t* orow = Mixed + row * DM + 256 + hd * 64;
; #pragma unroll
;             for (int g4 = 0; g4 < 4; ++g4) {
;                 const int dv = 8 * g4 + 4 * h; const f32x4 ga = *(const f32x4*)(gain + hd * 64 + dv), gb = *(const f32x4*)(gain + hd * 64 + 32 + dv);
;                 u32x2 wa, wb;
;                 wa.x = pk2(oa0[4 * g4 + 0] * rn * ga.x, oa0[4 * g4 + 1] * rn * ga.y); wa.y = pk2(oa0[4 * g4 + 2] * rn * ga.z, oa0[4 * g4 + 3] * rn * ga.w);
;                 wb.x = pk2(oa1[4 * g4 + 0] * rn * gb.x, oa1[4 * g4 + 1] * rn * gb.y); wb.y = pk2(oa1[4 * g4 + 2] * rn * gb.z, oa1[4 * g4 + 3] * rn * gb.w);
;                 *(u32x2*)(orow + dv) = wa; *(u32x2*)(orow + 32 + dv) = wb;
;             }
	v_add_f32_e32 v40, v40, v41
	v_fmamk_f32 v40, v40, 0x3c800000, v238
	v_mul_f32_e32 v41, 0x4b800000, v40
	v_cmp_gt_f32_e32 vcc, s63, v40
	v_lshl_add_u64 v[66:67], v[38:39], 0, s[6:7]
	s_mov_b64 s[6:7], 0
	v_cndmask_b32_e32 v40, v40, v41, vcc
	v_rsq_f32_e32 v40, v40
	s_nop 0
	v_mul_f32_e32 v41, 0x45800000, v40
	v_cndmask_b32_e32 v40, v40, v41, vcc
	v_mul_f32_e32 v68, v179, v40
	v_pk_mul_f32 v[34:35], v[34:35], v[68:69] op_sel_hi:[1,0]
	v_pk_mul_f32 v[36:37], v[36:37], v[68:69] op_sel_hi:[1,0]
	s_waitcnt vmcnt(1)
	v_pk_mul_f32 v[34:35], v[98:99], v[34:35]
	v_pk_mul_f32 v[36:37], v[100:101], v[36:37]
	v_cvt_pk_bf16_f32 v34, v34, v35
	v_cvt_pk_bf16_f32 v35, v36, v37
	v_pk_mul_f32 v[36:37], v[50:51], v[68:69] op_sel_hi:[1,0]
	v_pk_mul_f32 v[40:41], v[52:53], v[68:69] op_sel_hi:[1,0]
	v_add_co_u32_e32 v38, vcc, s53, v38
	s_waitcnt vmcnt(0)
	v_pk_mul_f32 v[36:37], v[94:95], v[36:37]
	v_pk_mul_f32 v[40:41], v[96:97], v[40:41]
	v_addc_co_u32_e32 v39, vcc, 0, v39, vcc
	v_cvt_pk_bf16_f32 v36, v36, v37
	v_cvt_pk_bf16_f32 v37, v40, v41
	global_store_dwordx2 v[38:39], v[34:35], off offset:512
	global_store_dwordx2 v[66:67], v[36:37], off offset:64
	global_load_dwordx4 v[34:37], v[216:217], off offset:32
	s_nop 0
	global_load_dwordx4 v[38:41], v[216:217], off offset:160
	v_pk_mul_f32 v[50:51], v[72:73], v[68:69] op_sel_hi:[1,0]
	v_pk_mul_f32 v[52:53], v[70:71], v[68:69] op_sel_hi:[1,0]
	v_pk_mul_f32 v[54:55], v[54:55], v[68:69] op_sel_hi:[1,0]
	v_pk_mul_f32 v[56:57], v[56:57], v[68:69] op_sel_hi:[1,0]
	v_pk_mul_f32 v[42:43], v[42:43], v[68:69] op_sel_hi:[1,0]
	v_pk_mul_f32 v[44:45], v[44:45], v[68:69] op_sel_hi:[1,0]
	s_and_b64 vcc, exec, s[2:3]
	s_waitcnt vmcnt(1)
	v_pk_mul_f32 v[34:35], v[34:35], v[50:51]
	v_pk_mul_f32 v[36:37], v[36:37], v[52:53]
	s_waitcnt vmcnt(0)
	v_pk_mul_f32 v[38:39], v[38:39], v[54:55]
	v_pk_mul_f32 v[40:41], v[40:41], v[56:57]
	v_cvt_pk_bf16_f32 v34, v34, v35
	v_cvt_pk_bf16_f32 v35, v36, v37
	v_cvt_pk_bf16_f32 v36, v38, v39
	v_cvt_pk_bf16_f32 v37, v40, v41
	global_store_dwordx2 v[66:67], v[34:35], off offset:16
	global_store_dwordx2 v[66:67], v[36:37], off offset:80
	global_load_dwordx4 v[34:37], v[216:217], off offset:64
	s_nop 0
	global_load_dwordx4 v[38:41], v[216:217], off offset:192
	v_pk_mul_f32 v[50:51], v[58:59], v[68:69] op_sel_hi:[1,0]
	v_pk_mul_f32 v[52:53], v[60:61], v[68:69] op_sel_hi:[1,0]
	s_waitcnt vmcnt(1)
	v_pk_mul_f32 v[34:35], v[34:35], v[42:43]
	v_pk_mul_f32 v[36:37], v[36:37], v[44:45]
	s_waitcnt vmcnt(0)
	v_pk_mul_f32 v[38:39], v[50:51], v[38:39]
	v_pk_mul_f32 v[40:41], v[52:53], v[40:41]
	v_cvt_pk_bf16_f32 v34, v34, v35
	v_cvt_pk_bf16_f32 v35, v36, v37
	v_cvt_pk_bf16_f32 v36, v38, v39
	v_cvt_pk_bf16_f32 v37, v40, v41
	global_store_dwordx2 v[66:67], v[34:35], off offset:32
	global_store_dwordx2 v[66:67], v[36:37], off offset:96
	global_load_dwordx4 v[34:37], v[216:217], off offset:96
	s_nop 0
	global_load_dwordx4 v[38:41], v[216:217], off offset:224
	v_pk_mul_f32 v[42:43], v[46:47], v[68:69] op_sel_hi:[1,0]
	v_pk_mul_f32 v[44:45], v[48:49], v[68:69] op_sel_hi:[1,0]
	v_pk_mul_f32 v[46:47], v[62:63], v[68:69] op_sel_hi:[1,0]
	v_pk_mul_f32 v[48:49], v[64:65], v[68:69] op_sel_hi:[1,0]
	s_waitcnt vmcnt(1)
	v_pk_mul_f32 v[34:35], v[42:43], v[34:35]
	v_pk_mul_f32 v[36:37], v[44:45], v[36:37]
	s_waitcnt vmcnt(0)
	v_pk_mul_f32 v[38:39], v[46:47], v[38:39]
	v_pk_mul_f32 v[40:41], v[48:49], v[40:41]
	v_cvt_pk_bf16_f32 v34, v34, v35
	v_cvt_pk_bf16_f32 v35, v36, v37
	v_cvt_pk_bf16_f32 v36, v38, v39
	v_cvt_pk_bf16_f32 v37, v40, v41
	global_store_dwordx2 v[66:67], v[34:35], off offset:48
	global_store_dwordx2 v[66:67], v[36:37], off offset:112
	s_cbranch_vccnz .LBB0_231

; #define LAS __attribute__((address_space(3)))
; __device__ __forceinline__ int rowi32(int i, int h) { return (i & 3) + 8 * (i >> 2) + 4 * h; }
; #define TL_BEGIN(Kg, kpitch, Vg, vpitch, t0, t1) do { TL_FETCH(Kg, kpitch, Vg, vpitch, t0); TL_WRITE(0); __syncthreads(); if ((t0) + 1 < (t1)) TL_FETCH(Kg, kpitch, Vg, vpitch, (t0) + 1); } while (0)
; __device__ __forceinline__ void attn_fast_x2(float mr1, f32x16& L1, f32x16& oa0, f32x16& oa1, float mr2, f32x16& L2, f32x16& ob0, f32x16& ob1, ...
;     f32x16 s1, s2;
; #pragma unroll
;     for (int i = 0; i < 16; ++i) { s1[i] = -mr1; s2[i] = -mr2; }
; #pragma unroll
;     for (int ks = 0; ks < 2; ++ks) { const bf16x8 a1 = *(const LAS bf16x8*)(Ks + (kr0 + r) * KP + 16 * ks + 8 * h), a2 = *(const LAS bf16x8*)(Ks + (kr0 + r) * KP + 32 + 16 * ks + 8 * h);
;         s1 = __builtin_amdgcn_mfma_f32_32x32x16_bf16(a1, qf1[ks], s1, 0, 0, 0); s2 = __builtin_amdgcn_mfma_f32_32x32x16_bf16(a2, qf2[ks], s2, 0, 0, 0); }
;     if (need_mask) {
; #pragma unroll
;         for (int i = 0; i < 16; ++i) { const bool ok = (key0 + rowi32(i, h)) <= qpos; s1[i] = ok ? s1[i] : NEG; s2[i] = ok ? s2[i] : NEG; }
;     }
; __device__ __forceinline__ void phase_da(const Params& p, int layer, LAS unsigned char* lds, const bf16_t* Z, bf16_t* Mixed, int tid, int wid, int lane) {
;     ...
;             TL_BEGIN(Kg, ZLD, Vg, ZLD, 0, ntile);
;             for (int t = 0, bi = 0; t < ntile; ++t, bi ^= 1) {
;                 const LAS bf16_t* Ks = Ks0 + bi * TLB; const LAS bf16_t* Vt = Ks + 64 * KP;
; #pragma unroll
;                 for (int sub = 0; sub < 2; ++sub) {
;                     const int k0 = 64 * t + 32 * sub;
;                     if (k0 > q0w + 31) continue;
;                     const bool nm = (k0 + 31 > q0w);
;                     if (t == 0 && sub == 0) {
;                         attn_sub_x2(m1, l1, oa0, oa1, m2, l2, ob0, ob1, qf1, qf2, Ks, Vt, 0, k0, qpos, 1.0f, nm, r, h);
;                         l1 += __shfl_xor(l1, 32); l2 += __shfl_xor(l2, 32);
; #pragma unroll
;                         for (int i = 0; i < 16; ++i) { L1[i] = l1; L2[i] = l2; }
;                     } else attn_fast_x2(m1, L1, oa0, oa1, m2, L2, ob0, ob1, qf1, qf2, Ks, Vt, 32 * sub, k0, qpos, nm, r, h);
.LBB0_247:
	s_waitcnt vmcnt(0)
	ds_write_b128 v250, v[134:137] offset:18432
	ds_write_b16 v252, v130 offset:27648
	ds_write_b16_d16_hi v252, v130 offset:27792
	ds_write_b16 v252, v131 offset:27936
	ds_write_b16_d16_hi v252, v131 offset:28080
	ds_write_b16 v252, v132 offset:28224
	ds_write_b16_d16_hi v252, v132 offset:28368
	ds_write_b16 v252, v133 offset:28512
	ds_write_b16_d16_hi v175, v133 offset:27648
	global_load_dwordx4 v[168:171], v[218:219], off offset:2560
	global_load_dwordx4 v[164:167], v[220:221], off
	s_lshl_b32 s6, s19, 2
	s_add_i32 s6, s6, 4
	s_add_i32 s19, s18, 0x80
	s_mov_b32 s20, 1
	s_mov_b32 s23, 0
	s_mov_b32 s21, 3
	v_mov_b64_e32 v[234:235], v[226:227]
	v_mov_b64_e32 v[236:237], v[224:225]
	v_lshlrev_b32_e32 v140, 4, v187
	v_add_u32_e32 v141, 0x19000, v140
	v_add_u32_e32 v140, 0x9000, v140
	ds_write_b128 v140, v[190:193]
	ds_write_b128 v140, v[194:197] offset:8192
	ds_write_b128 v140, v[198:201] offset:16384
	ds_write_b128 v140, v[202:205] offset:24576
	ds_write_b128 v140, v[206:209] offset:32768
	ds_write_b128 v140, v[210:213] offset:40960
	ds_write_b128 v140, v[214:217] offset:49152
	ds_write_b128 v140, v[218:221] offset:57344
	ds_write_b128 v141, v[222:225]
	ds_write_b128 v141, v[226:229] offset:8192
	ds_write_b128 v141, v[242:245] offset:16384
	ds_write_b128 v141, v[172:175] offset:24576
	ds_write_b64 v141, v[238:239] offset:32768
	s_waitcnt lgkmcnt(0)
	v_mov_b32_e32 v238, v204
	v_mov_b32_e32 v239, v174
	v_xor_b32_e32 v206, 0x80000000, v232
	v_xor_b32_e32 v190, 0x80000000, v233
	v_mov_b32_e32 v222, 0x3f803f80
	v_mov_b32_e32 v207, v206
	v_mov_b32_e32 v208, v206
	v_mov_b32_e32 v209, v206
	v_mov_b32_e32 v210, v206
	v_mov_b32_e32 v211, v206
	v_mov_b32_e32 v212, v206
	v_mov_b32_e32 v213, v206
	v_mov_b32_e32 v214, v206
	v_mov_b32_e32 v215, v206
	v_mov_b32_e32 v216, v206
	v_mov_b32_e32 v217, v206
	v_mov_b32_e32 v218, v206
	v_mov_b32_e32 v219, v206
	v_mov_b32_e32 v220, v206
	v_mov_b32_e32 v221, v206
	v_mov_b32_e32 v191, v190
	v_mov_b32_e32 v192, v190
	v_mov_b32_e32 v193, v190
	v_mov_b32_e32 v194, v190
	v_mov_b32_e32 v195, v190
	v_mov_b32_e32 v196, v190
	v_mov_b32_e32 v197, v190
	v_mov_b32_e32 v198, v190
	v_mov_b32_e32 v199, v190
	v_mov_b32_e32 v200, v190
	v_mov_b32_e32 v201, v190
	v_mov_b32_e32 v202, v190
	v_mov_b32_e32 v203, v190
	v_mov_b32_e32 v204, v190
	v_mov_b32_e32 v205, v190
	v_mov_b32_e32 v223, v222
	v_mov_b32_e32 v224, v222
	v_mov_b32_e32 v225, v222
	s_barrier
.LBB0_248:
	s_mul_i32 s18, s20, 0x4800
	s_add_i32 s18, s18, 0
	s_add_i32 s22, s23, 64
	v_add_u32_e32 v181, s18, v253
	s_add_i32 s24, s23, 0x7f
	s_cmp_le_i32 s24, s17
	s_cbranch_scc1 .Lda_fast
	s_cmp_gt_i32 s22, s7
	s_cbranch_scc1 .LBB0_252
	v_lshl_add_u32 v189, v248, 1, v181
	ds_read_b128 v[108:111], v189
	ds_read_b128 v[100:103], v189 offset:32
	ds_read_b128 v[182:185], v189 offset:64
	ds_read_b128 v[104:107], v189 offset:96
	s_add_i32 s24, s23, 0x5f
	s_cmp_le_i32 s24, s17
	s_waitcnt lgkmcnt(3)
	v_mfma_f32_32x32x16_bf16 v[116:131], v[108:111], v[152:155], v[206:221]
	s_waitcnt lgkmcnt(2)
	v_mfma_f32_32x32x16_bf16 v[116:131], v[100:103], v[156:159], v[116:131]
	s_waitcnt lgkmcnt(1)
	v_mfma_f32_32x32x16_bf16 v[132:147], v[182:185], v[160:163], v[190:205]
	s_waitcnt lgkmcnt(0)
	v_mfma_f32_32x32x16_bf16 v[132:147], v[104:107], v[148:151], v[132:147]
	s_cbranch_scc1 .LBB0_251
	v_add_u32_e32 v99, s23, v186
	v_add_u32_e32 v100, 64, v99
	v_cmp_gt_i32_e32 vcc, v100, v230
	s_nop 3
	v_cndmask_b32_e32 v116, v116, v180, vcc
	s_nop 4
	v_cndmask_b32_e32 v132, v132, v180, vcc
	v_cmp_lt_i32_e32 vcc, v100, v230
	v_add_u32_e32 v100, 0x42, v99
	s_nop 0
	v_cndmask_b32_e32 v117, v180, v117, vcc
	v_cndmask_b32_e32 v133, v180, v133, vcc
	v_cmp_gt_i32_e32 vcc, v100, v230
	v_add_u32_e32 v100, 0x43, v99
	s_nop 0
	v_cndmask_b32_e32 v118, v118, v180, vcc
	v_cndmask_b32_e32 v134, v134, v180, vcc
	v_cmp_gt_i32_e32 vcc, v100, v230
	v_add_u32_e32 v100, 0x48, v99
	s_nop 0
	v_cndmask_b32_e32 v119, v119, v180, vcc
	v_cndmask_b32_e32 v135, v135, v180, vcc
	v_cmp_gt_i32_e32 vcc, v100, v230
	v_add_u32_e32 v100, 0x49, v99
	s_nop 0
	v_cndmask_b32_e32 v120, v120, v180, vcc
	v_cndmask_b32_e32 v136, v136, v180, vcc
	v_cmp_gt_i32_e32 vcc, v100, v230
	v_add_u32_e32 v100, 0x4a, v99
	s_nop 0
	v_cndmask_b32_e32 v121, v121, v180, vcc
	v_cndmask_b32_e32 v137, v137, v180, vcc
	v_cmp_gt_i32_e32 vcc, v100, v230
	v_add_u32_e32 v100, 0x4b, v99
	s_nop 0
	v_cndmask_b32_e32 v122, v122, v180, vcc
	v_cndmask_b32_e32 v138, v138, v180, vcc
	v_cmp_gt_i32_e32 vcc, v100, v230
	v_add_u32_e32 v100, 0x50, v99
	s_nop 0
	v_cndmask_b32_e32 v123, v123, v180, vcc
	v_cndmask_b32_e32 v139, v139, v180, vcc
	v_cmp_gt_i32_e32 vcc, v100, v230
	v_add_u32_e32 v100, 0x51, v99
	s_nop 0
	v_cndmask_b32_e32 v124, v124, v180, vcc
	v_cndmask_b32_e32 v140, v140, v180, vcc
	v_cmp_gt_i32_e32 vcc, v100, v230
	v_add_u32_e32 v100, 0x52, v99
	s_nop 0
	v_cndmask_b32_e32 v125, v125, v180, vcc
	v_cndmask_b32_e32 v141, v141, v180, vcc
	v_cmp_gt_i32_e32 vcc, v100, v230
	v_add_u32_e32 v100, 0x53, v99
	s_nop 0
	v_cndmask_b32_e32 v126, v126, v180, vcc
	v_cndmask_b32_e32 v142, v142, v180, vcc
	v_cmp_gt_i32_e32 vcc, v100, v230
	v_add_u32_e32 v100, 0x58, v99
	s_nop 0
	v_cndmask_b32_e32 v127, v127, v180, vcc
	v_cndmask_b32_e32 v143, v143, v180, vcc
	v_cmp_gt_i32_e32 vcc, v100, v230
	v_add_u32_e32 v100, 0x59, v99
	s_nop 0
	v_cndmask_b32_e32 v128, v128, v180, vcc
	v_cndmask_b32_e32 v144, v144, v180, vcc
	v_cmp_gt_i32_e32 vcc, v100, v230
	v_add_u32_e32 v100, 0x5a, v99
	v_add_u32_e32 v99, 0x5b, v99
	v_cndmask_b32_e32 v129, v129, v180, vcc
	v_cndmask_b32_e32 v145, v145, v180, vcc
	v_cmp_gt_i32_e32 vcc, v100, v230
	s_nop 1
	v_cndmask_b32_e32 v130, v130, v180, vcc
	v_cndmask_b32_e32 v146, v146, v180, vcc
	v_cmp_gt_i32_e32 vcc, v99, v230
	s_nop 1
	v_cndmask_b32_e32 v131, v131, v180, vcc
	v_cndmask_b32_e32 v147, v147, v180, vcc

.LBB0_258:
	s_xor_b32 s20, s20, 1
	s_mul_i32 s23, s20, 0x4800
	s_add_i32 s23, s23, 0
	v_add3_u32 v98, s23, v249, v238
	s_waitcnt vmcnt(1)
	ds_write_b128 v98, v[168:171]
	v_lshl_add_u32 v98, v251, 1, s23
	s_waitcnt vmcnt(0)
	ds_write_b16 v98, v164 offset:9216
	ds_write_b16_d16_hi v98, v164 offset:9360
	ds_write_b16 v98, v165 offset:9504
	ds_write_b16_d16_hi v98, v165 offset:9648
	ds_write_b16 v98, v166 offset:9792
	ds_write_b16_d16_hi v98, v166 offset:9936
	ds_write_b16 v98, v167 offset:10080
	v_lshl_add_u32 v98, v239, 1, s23
	s_cmp_ge_u32 s21, s6
	ds_write_b16_d16_hi v98, v167 offset:9216
	s_cbranch_scc1 .LBB0_260
	global_load_dwordx4 v[168:171], v[234:235], off
	global_load_dwordx4 v[164:167], v[236:237], off

; #define LAS __attribute__((address_space(3)))
; __device__ __forceinline__ void attn_fast_x2(float mr1, f32x16& L1, f32x16& oa0, f32x16& oa1, float mr2, f32x16& L2, f32x16& ob0, f32x16& ob1, ...
;     f32x16 s1, s2;
; #pragma unroll
;     for (int i = 0; i < 16; ++i) { s1[i] = -mr1; s2[i] = -mr2; }
; #pragma unroll
;     for (int ks = 0; ks < 2; ++ks) { const bf16x8 a1 = *(const LAS bf16x8*)(Ks + (kr0 + r) * KP + 16 * ks + 8 * h), a2 = *(const LAS bf16x8*)(Ks + (kr0 + r) * KP + 32 + 16 * ks + 8 * h);
;         s1 = __builtin_amdgcn_mfma_f32_32x32x16_bf16(a1, qf1[ks], s1, 0, 0, 0); s2 = __builtin_amdgcn_mfma_f32_32x32x16_bf16(a2, qf2[ks], s2, 0, 0, 0); }
;     if (need_mask) {
; #pragma unroll
;         for (int i = 0; i < 16; ++i) { const bool ok = (key0 + rowi32(i, h)) <= qpos; s1[i] = ok ? s1[i] : NEG; s2[i] = ok ? s2[i] : NEG; }
;     }
;     float p1[16], p2[16];
; #pragma unroll
;     for (int i = 0; i < 16; ++i) { p1[i] = ex2(s1[i]); p2[i] = ex2(s2[i]); }
;     const u32x4 onesu = {0x3f803f80u, 0x3f803f80u, 0x3f803f80u, 0x3f803f80u}; const bf16x8 ones = __builtin_bit_cast(bf16x8, onesu);
; #pragma unroll
;     for (int s2i = 0; s2i < 2; ++s2i) {
;         const bf16x8 pb1 = pack8(p1[8 * s2i + 0], p1[8 * s2i + 1], p1[8 * s2i + 2], p1[8 * s2i + 3], p1[8 * s2i + 4], p1[8 * s2i + 5], p1[8 * s2i + 6], p1[8 * s2i + 7]);
;         const bf16x8 pb2 = pack8(p2[8 * s2i + 0], p2[8 * s2i + 1], p2[8 * s2i + 2], p2[8 * s2i + 3], p2[8 * s2i + 4], p2[8 * s2i + 5], p2[8 * s2i + 6], p2[8 * s2i + 7]);
;         const LAS bf16_t* vp = Vt + r * VP + kr0 + 16 * s2i + 4 * h;
;         const u32x2 a0l = *(const LAS u32x2*)vp, a0h = *(const LAS u32x2*)(vp + 8);
;         const u32x2 a1l = *(const LAS u32x2*)(vp + 32 * VP), a1h = *(const LAS u32x2*)(vp + 32 * VP + 8);
;         const u32x4 v0 = {a0l.x, a0l.y, a0h.x, a0h.y}, v1 = {a1l.x, a1l.y, a1h.x, a1h.y};
;         oa0 = __builtin_amdgcn_mfma_f32_32x32x16_bf16(__builtin_bit_cast(bf16x8, v0), pb1, oa0, 0, 0, 0);
;         ob0 = __builtin_amdgcn_mfma_f32_32x32x16_bf16(__builtin_bit_cast(bf16x8, v0), pb2, ob0, 0, 0, 0);
;         oa1 = __builtin_amdgcn_mfma_f32_32x32x16_bf16(__builtin_bit_cast(bf16x8, v1), pb1, oa1, 0, 0, 0);
;         ob1 = __builtin_amdgcn_mfma_f32_32x32x16_bf16(__builtin_bit_cast(bf16x8, v1), pb2, ob1, 0, 0, 0);
;         L1 = __builtin_amdgcn_mfma_f32_32x32x16_bf16(ones, pb1, L1, 0, 0, 0);
.Lda_fast:
	v_lshl_add_u32 v189, v248, 1, v181
	v_lshlrev_b32_e32 v99, 1, v248
	v_add3_u32 v99, s18, v240, v99
	ds_read_b128 v[100:103], v189
	ds_read_b128 v[104:107], v189 offset:32
	ds_read_b128 v[108:111], v189 offset:64
	ds_read_b128 v[112:115], v189 offset:96
	ds_read_b128 v[182:185], v99
	ds_read_b128 v[226:229], v99 offset:32
	ds_read_b128 v[242:245], v99 offset:64
	ds_read_b128 v[172:175], v99 offset:96
	v_add_u32_e32 v98, v181, v248
	v_add_u32_e32 v181, 0x3000, v98
	v_add_u32_e32 v98, 0x2000, v98
	s_waitcnt lgkmcnt(7)
	v_mfma_f32_32x32x16_bf16 v[116:131], v[100:103], v[152:155], v[206:221]
	s_waitcnt lgkmcnt(6)
	v_mfma_f32_32x32x16_bf16 v[116:131], v[104:107], v[156:159], v[116:131]
	s_waitcnt lgkmcnt(5)
	v_mfma_f32_32x32x16_bf16 v[132:147], v[108:111], v[160:163], v[190:205]
	s_waitcnt lgkmcnt(4)
	v_mfma_f32_32x32x16_bf16 v[132:147], v[112:115], v[148:151], v[132:147]
	ds_read2_b64 v[100:103], v98 offset0:128 offset1:130
	ds_read2_b64 v[104:107], v181 offset0:192 offset1:194
	ds_read2_b64 v[108:111], v98 offset0:132 offset1:134
	ds_read2_b64 v[112:115], v181 offset0:196 offset1:198
	s_nop 3
	v_exp_f32_e32 v116, v116
	v_exp_f32_e32 v117, v117
	v_exp_f32_e32 v118, v118
	v_exp_f32_e32 v119, v119
	v_exp_f32_e32 v120, v120
	v_exp_f32_e32 v121, v121
	v_exp_f32_e32 v122, v122
	v_exp_f32_e32 v123, v123
	v_cvt_pk_bf16_f32 v116, v116, v117
	v_cvt_pk_bf16_f32 v117, v118, v119
	v_cvt_pk_bf16_f32 v118, v120, v121
	v_cvt_pk_bf16_f32 v119, v122, v123
	s_waitcnt lgkmcnt(2)
	s_nop 0
	v_mfma_f32_32x32x16_bf16 v[34:49], v[100:103], v[116:119], v[34:49]
	v_exp_f32_e32 v124, v124
	v_exp_f32_e32 v125, v125
	v_exp_f32_e32 v126, v126
	v_mfma_f32_32x32x16_bf16 v[66:81], v[104:107], v[116:119], v[66:81]
	v_exp_f32_e32 v127, v127
	v_exp_f32_e32 v128, v128
	v_exp_f32_e32 v129, v129
	v_mfma_f32_32x32x16_bf16 v[2:17], v[222:225], v[116:119], v[2:17]
	v_exp_f32_e32 v130, v130
	v_exp_f32_e32 v131, v131
	v_cvt_pk_bf16_f32 v120, v124, v125
	v_cvt_pk_bf16_f32 v121, v126, v127
	v_cvt_pk_bf16_f32 v122, v128, v129
	v_cvt_pk_bf16_f32 v123, v130, v131
	s_waitcnt lgkmcnt(0)
	s_nop 0
	v_mfma_f32_32x32x16_bf16 v[34:49], v[108:111], v[120:123], v[34:49]
	v_exp_f32_e32 v132, v132
	v_exp_f32_e32 v133, v133
	v_exp_f32_e32 v134, v134
	v_mfma_f32_32x32x16_bf16 v[66:81], v[112:115], v[120:123], v[66:81]
	v_exp_f32_e32 v135, v135
	v_exp_f32_e32 v136, v136
	v_exp_f32_e32 v137, v137
	v_mfma_f32_32x32x16_bf16 v[2:17], v[222:225], v[120:123], v[2:17]
	v_exp_f32_e32 v138, v138
	v_exp_f32_e32 v139, v139
	v_cvt_pk_bf16_f32 v132, v132, v133
	v_cvt_pk_bf16_f32 v133, v134, v135
	v_mfma_f32_32x32x16_bf16 v[116:131], v[182:185], v[152:155], v[206:221]
	v_cvt_pk_bf16_f32 v134, v136, v137
	v_cvt_pk_bf16_f32 v135, v138, v139
	v_exp_f32_e32 v140, v140
	v_exp_f32_e32 v141, v141
	v_mfma_f32_32x32x16_bf16 v[116:131], v[226:229], v[156:159], v[116:131]
	v_exp_f32_e32 v142, v142
	v_exp_f32_e32 v143, v143
	v_exp_f32_e32 v144, v144
	ds_read2_b64 v[182:185], v98 offset0:136 offset1:138
	ds_read2_b64 v[226:229], v181 offset0:200 offset1:202
	v_mfma_f32_32x32x16_bf16 v[82:97], v[100:103], v[132:135], v[82:97]
	v_exp_f32_e32 v145, v145
	v_exp_f32_e32 v146, v146
	v_exp_f32_e32 v147, v147
	v_mfma_f32_32x32x16_bf16 v[50:65], v[104:107], v[132:135], v[50:65]
	v_cvt_pk_bf16_f32 v136, v140, v141
	v_cvt_pk_bf16_f32 v137, v142, v143
	v_cvt_pk_bf16_f32 v138, v144, v145
	v_cvt_pk_bf16_f32 v139, v146, v147
	ds_read2_b64 v[100:103], v98 offset0:140 offset1:142
	ds_read2_b64 v[104:107], v181 offset0:204 offset1:206
	v_mfma_f32_32x32x16_bf16 v[18:33], v[222:225], v[132:135], v[18:33]
	v_exp_f32_e32 v116, v116
	v_exp_f32_e32 v117, v117
	v_exp_f32_e32 v118, v118
	v_mfma_f32_32x32x16_bf16 v[82:97], v[108:111], v[136:139], v[82:97]
	v_exp_f32_e32 v119, v119
	v_exp_f32_e32 v120, v120
	v_exp_f32_e32 v121, v121
	v_mfma_f32_32x32x16_bf16 v[50:65], v[112:115], v[136:139], v[50:65]
	v_exp_f32_e32 v122, v122
	v_exp_f32_e32 v123, v123
	v_cvt_pk_bf16_f32 v116, v116, v117
	v_cvt_pk_bf16_f32 v117, v118, v119
	v_mfma_f32_32x32x16_bf16 v[18:33], v[222:225], v[136:139], v[18:33]
	v_cvt_pk_bf16_f32 v118, v120, v121
	v_cvt_pk_bf16_f32 v119, v122, v123
	v_exp_f32_e32 v124, v124
	v_exp_f32_e32 v125, v125
	v_mfma_f32_32x32x16_bf16 v[132:147], v[242:245], v[160:163], v[190:205]
	v_exp_f32_e32 v126, v126
	v_exp_f32_e32 v127, v127
	v_exp_f32_e32 v128, v128
	v_mfma_f32_32x32x16_bf16 v[132:147], v[172:175], v[148:151], v[132:147]
	v_exp_f32_e32 v129, v129
	v_exp_f32_e32 v130, v130
	v_exp_f32_e32 v131, v131
	s_waitcnt lgkmcnt(2)
	v_mfma_f32_32x32x16_bf16 v[34:49], v[182:185], v[116:119], v[34:49]
	v_cvt_pk_bf16_f32 v120, v124, v125
	v_cvt_pk_bf16_f32 v121, v126, v127
	v_cvt_pk_bf16_f32 v122, v128, v129
	v_cvt_pk_bf16_f32 v123, v130, v131
	v_mfma_f32_32x32x16_bf16 v[66:81], v[226:229], v[116:119], v[66:81]
	s_nop 1
	v_exp_f32_e32 v132, v132
	v_exp_f32_e32 v133, v133
	v_exp_f32_e32 v134, v134
	v_mfma_f32_32x32x16_bf16 v[2:17], v[222:225], v[116:119], v[2:17]
	v_exp_f32_e32 v135, v135
	v_exp_f32_e32 v136, v136
	v_exp_f32_e32 v137, v137
	s_waitcnt lgkmcnt(0)
	v_mfma_f32_32x32x16_bf16 v[34:49], v[100:103], v[120:123], v[34:49]
	v_exp_f32_e32 v138, v138
	v_exp_f32_e32 v139, v139
	v_cvt_pk_bf16_f32 v132, v132, v133
	v_cvt_pk_bf16_f32 v133, v134, v135
	v_mfma_f32_32x32x16_bf16 v[66:81], v[104:107], v[120:123], v[66:81]
	v_cvt_pk_bf16_f32 v134, v136, v137
	v_cvt_pk_bf16_f32 v135, v138, v139
	v_exp_f32_e32 v140, v140
	v_exp_f32_e32 v141, v141
	v_mfma_f32_32x32x16_bf16 v[2:17], v[222:225], v[120:123], v[2:17]
	v_exp_f32_e32 v142, v142
	v_exp_f32_e32 v143, v143
	v_exp_f32_e32 v144, v144
	v_mfma_f32_32x32x16_bf16 v[82:97], v[182:185], v[132:135], v[82:97]
	v_exp_f32_e32 v145, v145
	v_exp_f32_e32 v146, v146
	v_exp_f32_e32 v147, v147
	v_mfma_f32_32x32x16_bf16 v[50:65], v[226:229], v[132:135], v[50:65]
	v_cvt_pk_bf16_f32 v136, v140, v141
	v_cvt_pk_bf16_f32 v137, v142, v143
	v_cvt_pk_bf16_f32 v138, v144, v145
	v_cvt_pk_bf16_f32 v139, v146, v147
	v_mfma_f32_32x32x16_bf16 v[18:33], v[222:225], v[132:135], v[18:33]
	s_nop 0
	v_mfma_f32_32x32x16_bf16 v[82:97], v[100:103], v[136:139], v[82:97]
	v_mfma_f32_32x32x16_bf16 v[50:65], v[104:107], v[136:139], v[50:65]
	v_mfma_f32_32x32x16_bf16 v[18:33], v[222:225], v[136:139], v[18:33]
	s_branch .LBB0_256

; __device__ __forceinline__ void phase_cmp(const Params& p, LAS unsigned char* lds, const bf16_t* Z, const float* G, const bf16_t* KC, const bf16_t* ACCW, float* ACC, int* IDX, ...
;     ...
; #pragma unroll
;                     for (int i = 0; i < 4; ++i) cnt += __builtin_popcountll(__ballot(ok[i] && v[i] >= trial));
;                     if (cnt >= 13) T = trial; }
.LBB0_433:
	s_lshl_b32 s20, 1, s22
	s_or_b32 s23, s20, s96
	s_waitcnt lgkmcnt(0)
	v_cmp_le_u32_e64 s[20:21], s23, v2
	v_cmp_le_u32_e64 s[98:99], s23, v5
	v_cmp_le_u32_e64 s[100:101], s23, v4
	s_and_b64 s[20:21], s[70:71], s[20:21]
	s_bcnt1_i32_b64 s24, s[20:21]
	v_cmp_le_u32_e64 s[20:21], s23, v0
	s_and_b64 s[98:99], vcc, s[98:99]
	s_bcnt1_i32_b64 s25, s[98:99]
	s_add_i32 s24, s24, s25
	s_and_b64 s[100:101], s[16:17], s[100:101]
	s_bcnt1_i32_b64 s25, s[100:101]
	s_add_i32 s24, s24, s25
	s_and_b64 s[20:21], s[18:19], s[20:21]
	s_bcnt1_i32_b64 s25, s[20:21]
	s_add_i32 s24, s24, s25
	s_cmp_gt_u32 s24, 12
	s_cselect_b32 s96, s23, s96
	s_add_i32 s22, s22, -1
	s_cmp_eq_u32 s22, -1
	s_cbranch_scc0 .LBB0_433
	v_cmp_lt_u32_e64 s[20:21], s96, v2
	s_and_b64 s[80:81], s[70:71], s[20:21]
	v_cmp_lt_u32_e64 s[20:21], s96, v5
	s_and_b64 s[78:79], vcc, s[20:21]
	v_cmp_lt_u32_e64 s[20:21], s96, v4
	s_and_b64 s[76:77], s[16:17], s[20:21]
	v_cmp_lt_u32_e64 s[20:21], s96, v0
	s_and_b64 s[74:75], s[18:19], s[20:21]
	s_ashr_i32 s21, s95, 31
	s_add_u32 s20, s95, s26
	s_addc_u32 s21, s21, 0
	s_lshl_b64 s[20:21], s[20:21], 7
	v_cndmask_b32_e64 v3, 0, 1, s[80:81]
	v_cndmask_b32_e64 v8, 0, 1, s[78:79]
	v_cndmask_b32_e64 v7, 0, 1, s[76:77]
	v_cndmask_b32_e64 v6, 0, 1, s[74:75]
	s_add_u32 s72, s92, s20
	v_cmp_ne_u32_e64 s[22:23], 0, v3
	v_cmp_ne_u32_e64 s[24:25], 0, v8
	v_cmp_ne_u32_e64 s[38:39], 0, v7
	v_cmp_ne_u32_e64 s[40:41], 0, v6
	s_addc_u32 s73, s93, s21
	s_and_saveexec_b64 s[20:21], s[8:9]
	s_cbranch_execz .LBB0_436
	v_mov_b32_e32 v11, s94
	v_mov_b32_e32 v12, s91
	v_mov_b32_e32 v10, v1
	global_store_dwordx3 v1, v[10:12], s[72:73]

; #define LAS __attribute__((address_space(3)))
; __global__ void __launch_bounds__(512, 2) hybrid_fwd(Params p_unused) {
;     extern __shared__ __attribute__((aligned(16))) unsigned char lds_raw[];
;     LAS unsigned char* lds = (LAS unsigned char*)lds_raw;
;     cg::grid_group grid = cg::this_grid();
;     const int tid0 = threadIdx.x;
;     KArgP kargs = (KArgP)__builtin_amdgcn_kernarg_segment_ptr();
	.amdhsa_kernel _Z10hybrid_fwd6Params
		.amdhsa_group_segment_fixed_size 0
		.amdhsa_private_segment_fixed_size 0
		.amdhsa_kernarg_size 424
		.amdhsa_user_sgpr_count 2
		.amdhsa_user_sgpr_dispatch_ptr 0
		.amdhsa_user_sgpr_queue_ptr 0
		.amdhsa_user_sgpr_kernarg_segment_ptr 1
		.amdhsa_user_sgpr_dispatch_id 0
		.amdhsa_user_sgpr_kernarg_preload_length 0
		.amdhsa_user_sgpr_kernarg_preload_offset 0
		.amdhsa_user_sgpr_private_segment_size 0
		.amdhsa_uses_dynamic_stack 0
		.amdhsa_enable_private_segment 0
		.amdhsa_system_sgpr_workgroup_id_x 1
		.amdhsa_system_sgpr_workgroup_id_y 0
		.amdhsa_system_sgpr_workgroup_id_z 0
		.amdhsa_system_sgpr_workgroup_info 0
		.amdhsa_system_vgpr_workitem_id 2
		.amdhsa_next_free_vgpr 256
		.amdhsa_next_free_sgpr 102
		.amdhsa_accum_offset 256
		.amdhsa_reserve_vcc 1
		.amdhsa_float_round_mode_32 0
		.amdhsa_float_round_mode_16_64 0
		.amdhsa_float_denorm_mode_32 3
		.amdhsa_float_denorm_mode_16_64 3
		.amdhsa_dx10_clamp 1
		.amdhsa_ieee_mode 1
		.amdhsa_fp16_overflow 0
		.amdhsa_tg_split 0
		.amdhsa_exception_fp_ieee_invalid_op 0
		.amdhsa_exception_fp_denorm_src 0
		.amdhsa_exception_fp_ieee_div_zero 0
		.amdhsa_exception_fp_ieee_overflow 0
		.amdhsa_exception_fp_ieee_underflow 0
		.amdhsa_exception_fp_ieee_inexact 0
		.amdhsa_exception_int_div_zero 0
	.end_amdhsa_kernel

; #define LAS __attribute__((address_space(3)))
; __global__ void __launch_bounds__(512, 2) hybrid_fwd(Params p_unused) {
;     extern __shared__ __attribute__((aligned(16))) unsigned char lds_raw[];
;     LAS unsigned char* lds = (LAS unsigned char*)lds_raw;
;     cg::grid_group grid = cg::this_grid();
;     const int tid0 = threadIdx.x;
;     KArgP kargs = (KArgP)__builtin_amdgcn_kernarg_segment_ptr();
amdhsa.kernels:
  - .agpr_count:     0
    .args:
      - .offset:         0
        .size:           168
        .value_kind:     by_value
      - .offset:         168
        .size:           4
        .value_kind:     hidden_block_count_x
      - .offset:         172
        .size:           4
        .value_kind:     hidden_block_count_y
      - .offset:         176
        .size:           4
        .value_kind:     hidden_block_count_z
      - .offset:         180
        .size:           2
        .value_kind:     hidden_group_size_x
      - .offset:         182
        .size:           2
        .value_kind:     hidden_group_size_y
      - .offset:         184
        .size:           2
        .value_kind:     hidden_group_size_z
      - .offset:         186
        .size:           2
        .value_kind:     hidden_remainder_x
      - .offset:         188
        .size:           2
        .value_kind:     hidden_remainder_y
      - .offset:         190
        .size:           2
        .value_kind:     hidden_remainder_z
      - .offset:         208
        .size:           8
        .value_kind:     hidden_global_offset_x
      - .offset:         216
        .size:           8
        .value_kind:     hidden_global_offset_y
      - .offset:         224
        .size:           8
        .value_kind:     hidden_global_offset_z
      - .offset:         232
        .size:           2
        .value_kind:     hidden_grid_dims
      - .offset:         256
        .size:           8
        .value_kind:     hidden_multigrid_sync_arg
      - .offset:         288
        .size:           4
        .value_kind:     hidden_dynamic_lds_size
    .group_segment_fixed_size: 0
    .kernarg_segment_align: 8
    .kernarg_segment_size: 424
    .language:       OpenCL C
    .language_version:
      - 2
      - 0
    .max_flat_workgroup_size: 512
    .name:           _Z10hybrid_fwd6Params
    .private_segment_fixed_size: 0
    .sgpr_count:     108
    .sgpr_spill_count: 129
    .symbol:         _Z10hybrid_fwd6Params.kd
    .uniform_work_group_size: 1
    .uses_dynamic_stack: false
    .vgpr_count:     256
    .vgpr_spill_count: 0
    .wavefront_size: 64
